# v82 plus the in-projection plain-section stores use the SGPR-base + 32-bit VGPR offset form instead of 64-bit VGPR addresses
# baseline (speedup 1.0000x reference)
.Lpeelx0:
	s_lshl_b32 s7, s34, 8
	s_cmp_lt_i32 s35, 28
	s_mov_b64 s[4:5], -1
	s_cbranch_scc0 .LBB0_431
	s_add_i32 s16, s7, s27
	v_or_b32_e32 v207, s16, v192
	s_cmp_gt_i32 s35, 3
	s_cbranch_scc0 .LBB0_411
	s_add_i32 s4, s35, -12
	s_cmp_gt_u32 s4, 7
	s_mov_b64 s[4:5], -1
	s_cbranch_scc0 .LBB0_408
	s_waitcnt lgkmcnt(0)
	s_lshl_b32 s4, s35, 8
	s_add_i32 s5, s4, 0xfffffc00
	s_cmp_lt_u32 s35, 12
	s_cselect_b32 s4, s4, s5
	v_and_b32_e32 v11, 8, v220
	v_cmp_ne_u32_e32 vcc, 0, v11
	v_bfe_u32 v10, v220, 3, 3
	v_and_b32_e32 v12, 0x60, v194
	v_lshlrev_b32_e32 v12, 1, v12
	v_and_b32_e32 v13, 7, v220
	v_lshl_or_b32 v12, v13, 3, v12
	v_or_b32_e32 v32, s4, v12
	v_or_b32_e32 v14, s16, v10
	v_mul_lo_u32 v0, v14, s33
	v_lshl_add_u32 v16, v32, 1, v0
	v_and_b32_e32 v13, 4, v220
	v_lshl_or_b32 v13, v13, 1, v10
	v_and_b32_e32 v12, 3, v220
	v_lshl_or_b32 v13, v12, 4, v13
	v_lshlrev_b32_e32 v13, 2, v13
	v_add_u32_e32 v17, 0x30000, v16
	v_add_u32_e32 v18, 0x30000, v17
	v_add_u32_e32 v19, 0x30000, v18
	v_add_u32_e32 v20, 0x180000, v16
	v_add_u32_e32 v21, 0x30000, v20
	v_add_u32_e32 v22, 0x30000, v21
	v_add_u32_e32 v23, 0x30000, v22
	v_cvt_pk_f16_f32 v158, v158, v159
	v_cvt_pk_f16_f32 v159, v160, v161
	v_cvt_pk_f16_f32 v160, v142, v143
	v_cvt_pk_f16_f32 v161, v144, v145
	v_cvt_pk_f16_f32 v94, v94, v95
	v_cvt_pk_f16_f32 v95, v96, v97
	v_cvt_pk_f16_f32 v96, v78, v79
	v_cvt_pk_f16_f32 v97, v80, v81
	v_mov_b32_dpp v0, v158 row_ror:8 row_mask:0xf bank_mask:0xf
	v_mov_b32_dpp v1, v159 row_ror:8 row_mask:0xf bank_mask:0xf
	v_mov_b32_dpp v2, v160 row_ror:8 row_mask:0xf bank_mask:0xf
	v_mov_b32_dpp v3, v161 row_ror:8 row_mask:0xf bank_mask:0xf
	v_mov_b32_dpp v4, v94 row_ror:8 row_mask:0xf bank_mask:0xf
	v_mov_b32_dpp v5, v95 row_ror:8 row_mask:0xf bank_mask:0xf
	v_mov_b32_dpp v6, v96 row_ror:8 row_mask:0xf bank_mask:0xf
	v_mov_b32_dpp v7, v97 row_ror:8 row_mask:0xf bank_mask:0xf
	v_cndmask_b32_e32 v158, v158, v4, vcc
	v_cndmask_b32_e32 v159, v159, v5, vcc
	v_cndmask_b32_e32 v160, v160, v6, vcc
	v_cndmask_b32_e32 v161, v161, v7, vcc
	v_cndmask_b32_e32 v94, v0, v94, vcc
	v_cndmask_b32_e32 v95, v1, v95, vcc
	v_cndmask_b32_e32 v96, v2, v96, vcc
	v_cndmask_b32_e32 v97, v3, v97, vcc
	ds_bpermute_b32 v158, v13, v158
	ds_bpermute_b32 v159, v13, v159
	ds_bpermute_b32 v160, v13, v160
	ds_bpermute_b32 v161, v13, v161
	ds_bpermute_b32 v94, v13, v94
	ds_bpermute_b32 v95, v13, v95
	ds_bpermute_b32 v96, v13, v96
	ds_bpermute_b32 v97, v13, v97
	v_cvt_pk_f16_f32 v150, v150, v151
	v_cvt_pk_f16_f32 v151, v152, v153
	v_cvt_pk_f16_f32 v152, v134, v135
	v_cvt_pk_f16_f32 v153, v136, v137
	v_cvt_pk_f16_f32 v86, v86, v87
	v_cvt_pk_f16_f32 v87, v88, v89
	v_cvt_pk_f16_f32 v88, v70, v71
	v_cvt_pk_f16_f32 v89, v72, v73
	v_mov_b32_dpp v0, v150 row_ror:8 row_mask:0xf bank_mask:0xf
	v_mov_b32_dpp v1, v151 row_ror:8 row_mask:0xf bank_mask:0xf
	v_mov_b32_dpp v2, v152 row_ror:8 row_mask:0xf bank_mask:0xf
	v_mov_b32_dpp v3, v153 row_ror:8 row_mask:0xf bank_mask:0xf
	v_mov_b32_dpp v4, v86 row_ror:8 row_mask:0xf bank_mask:0xf
	v_mov_b32_dpp v5, v87 row_ror:8 row_mask:0xf bank_mask:0xf
	v_mov_b32_dpp v6, v88 row_ror:8 row_mask:0xf bank_mask:0xf
	v_mov_b32_dpp v7, v89 row_ror:8 row_mask:0xf bank_mask:0xf
	v_cndmask_b32_e32 v150, v150, v4, vcc
	v_cndmask_b32_e32 v151, v151, v5, vcc
	v_cndmask_b32_e32 v152, v152, v6, vcc
	v_cndmask_b32_e32 v153, v153, v7, vcc
	v_cndmask_b32_e32 v86, v0, v86, vcc
	v_cndmask_b32_e32 v87, v1, v87, vcc
	v_cndmask_b32_e32 v88, v2, v88, vcc
	v_cndmask_b32_e32 v89, v3, v89, vcc
	ds_bpermute_b32 v150, v13, v150
	ds_bpermute_b32 v151, v13, v151
	ds_bpermute_b32 v152, v13, v152
	ds_bpermute_b32 v153, v13, v153
	ds_bpermute_b32 v86, v13, v86
	ds_bpermute_b32 v87, v13, v87
	ds_bpermute_b32 v88, v13, v88
	ds_bpermute_b32 v89, v13, v89
	s_waitcnt lgkmcnt(8)
	v_add_u32_e32 v10, 0x18000, v16
	global_store_dwordx4 v16, v[158:161], s[70:71]
	global_store_dwordx4 v10, v[94:97], s[70:71]
	v_cvt_pk_f16_f32 v154, v154, v155
	v_cvt_pk_f16_f32 v155, v156, v157
	v_cvt_pk_f16_f32 v156, v138, v139
	v_cvt_pk_f16_f32 v157, v140, v141
	v_cvt_pk_f16_f32 v90, v90, v91
	v_cvt_pk_f16_f32 v91, v92, v93
	v_cvt_pk_f16_f32 v92, v74, v75
	v_cvt_pk_f16_f32 v93, v76, v77
	v_mov_b32_dpp v0, v154 row_ror:8 row_mask:0xf bank_mask:0xf
	v_mov_b32_dpp v1, v155 row_ror:8 row_mask:0xf bank_mask:0xf
	v_mov_b32_dpp v2, v156 row_ror:8 row_mask:0xf bank_mask:0xf
	v_mov_b32_dpp v3, v157 row_ror:8 row_mask:0xf bank_mask:0xf
	v_mov_b32_dpp v4, v90 row_ror:8 row_mask:0xf bank_mask:0xf
	v_mov_b32_dpp v5, v91 row_ror:8 row_mask:0xf bank_mask:0xf
	v_mov_b32_dpp v6, v92 row_ror:8 row_mask:0xf bank_mask:0xf
	v_mov_b32_dpp v7, v93 row_ror:8 row_mask:0xf bank_mask:0xf
	v_cndmask_b32_e32 v154, v154, v4, vcc
	v_cndmask_b32_e32 v155, v155, v5, vcc
	v_cndmask_b32_e32 v156, v156, v6, vcc
	v_cndmask_b32_e32 v157, v157, v7, vcc
	v_cndmask_b32_e32 v90, v0, v90, vcc
	v_cndmask_b32_e32 v91, v1, v91, vcc
	v_cndmask_b32_e32 v92, v2, v92, vcc
	v_cndmask_b32_e32 v93, v3, v93, vcc
	ds_bpermute_b32 v154, v13, v154
	ds_bpermute_b32 v155, v13, v155
	ds_bpermute_b32 v156, v13, v156
	ds_bpermute_b32 v157, v13, v157
	ds_bpermute_b32 v90, v13, v90
	ds_bpermute_b32 v91, v13, v91
	ds_bpermute_b32 v92, v13, v92
	ds_bpermute_b32 v93, v13, v93
	s_waitcnt lgkmcnt(8)
	v_add_u32_e32 v10, 0x18000, v17
	global_store_dwordx4 v17, v[150:153], s[70:71]
	global_store_dwordx4 v10, v[86:89], s[70:71]
	v_cvt_pk_f16_f32 v146, v146, v147
	v_cvt_pk_f16_f32 v147, v148, v149
	v_cvt_pk_f16_f32 v148, v130, v131
	v_cvt_pk_f16_f32 v149, v132, v133
	v_cvt_pk_f16_f32 v82, v82, v83
	v_cvt_pk_f16_f32 v83, v84, v85
	v_cvt_pk_f16_f32 v84, v66, v67
	v_cvt_pk_f16_f32 v85, v68, v69
	v_mov_b32_dpp v0, v146 row_ror:8 row_mask:0xf bank_mask:0xf
	v_mov_b32_dpp v1, v147 row_ror:8 row_mask:0xf bank_mask:0xf
	v_mov_b32_dpp v2, v148 row_ror:8 row_mask:0xf bank_mask:0xf
	v_mov_b32_dpp v3, v149 row_ror:8 row_mask:0xf bank_mask:0xf
	v_mov_b32_dpp v4, v82 row_ror:8 row_mask:0xf bank_mask:0xf
	v_mov_b32_dpp v5, v83 row_ror:8 row_mask:0xf bank_mask:0xf
	v_mov_b32_dpp v6, v84 row_ror:8 row_mask:0xf bank_mask:0xf
	v_mov_b32_dpp v7, v85 row_ror:8 row_mask:0xf bank_mask:0xf
	v_cndmask_b32_e32 v146, v146, v4, vcc
	v_cndmask_b32_e32 v147, v147, v5, vcc
	v_cndmask_b32_e32 v148, v148, v6, vcc
	v_cndmask_b32_e32 v149, v149, v7, vcc
	v_cndmask_b32_e32 v82, v0, v82, vcc
	v_cndmask_b32_e32 v83, v1, v83, vcc
	v_cndmask_b32_e32 v84, v2, v84, vcc
	v_cndmask_b32_e32 v85, v3, v85, vcc
	ds_bpermute_b32 v146, v13, v146
	ds_bpermute_b32 v147, v13, v147
	ds_bpermute_b32 v148, v13, v148
	ds_bpermute_b32 v149, v13, v149
	ds_bpermute_b32 v82, v13, v82
	ds_bpermute_b32 v83, v13, v83
	ds_bpermute_b32 v84, v13, v84
	ds_bpermute_b32 v85, v13, v85
	s_waitcnt lgkmcnt(8)
	v_add_u32_e32 v10, 0x18000, v18
	global_store_dwordx4 v18, v[154:157], s[70:71]
	global_store_dwordx4 v10, v[90:93], s[70:71]
	v_cvt_pk_f16_f32 v126, v126, v127
	v_cvt_pk_f16_f32 v127, v128, v129
	v_cvt_pk_f16_f32 v128, v110, v111
	v_cvt_pk_f16_f32 v129, v112, v113
	v_cvt_pk_f16_f32 v62, v62, v63
	v_cvt_pk_f16_f32 v63, v64, v65
	v_cvt_pk_f16_f32 v64, v46, v47
	v_cvt_pk_f16_f32 v65, v48, v49
	v_mov_b32_dpp v0, v126 row_ror:8 row_mask:0xf bank_mask:0xf
	v_mov_b32_dpp v1, v127 row_ror:8 row_mask:0xf bank_mask:0xf
	v_mov_b32_dpp v2, v128 row_ror:8 row_mask:0xf bank_mask:0xf
	v_mov_b32_dpp v3, v129 row_ror:8 row_mask:0xf bank_mask:0xf
	v_mov_b32_dpp v4, v62 row_ror:8 row_mask:0xf bank_mask:0xf
	v_mov_b32_dpp v5, v63 row_ror:8 row_mask:0xf bank_mask:0xf
	v_mov_b32_dpp v6, v64 row_ror:8 row_mask:0xf bank_mask:0xf
	v_mov_b32_dpp v7, v65 row_ror:8 row_mask:0xf bank_mask:0xf
	v_cndmask_b32_e32 v126, v126, v4, vcc
	v_cndmask_b32_e32 v127, v127, v5, vcc
	v_cndmask_b32_e32 v128, v128, v6, vcc
	v_cndmask_b32_e32 v129, v129, v7, vcc
	v_cndmask_b32_e32 v62, v0, v62, vcc
	v_cndmask_b32_e32 v63, v1, v63, vcc
	v_cndmask_b32_e32 v64, v2, v64, vcc
	v_cndmask_b32_e32 v65, v3, v65, vcc
	ds_bpermute_b32 v126, v13, v126
	ds_bpermute_b32 v127, v13, v127
	ds_bpermute_b32 v128, v13, v128
	ds_bpermute_b32 v129, v13, v129
	ds_bpermute_b32 v62, v13, v62
	ds_bpermute_b32 v63, v13, v63
	ds_bpermute_b32 v64, v13, v64
	ds_bpermute_b32 v65, v13, v65
	s_waitcnt lgkmcnt(8)
	v_add_u32_e32 v10, 0x18000, v19
	global_store_dwordx4 v19, v[146:149], s[70:71]
	global_store_dwordx4 v10, v[82:85], s[70:71]
	v_cvt_pk_f16_f32 v118, v118, v119
	v_cvt_pk_f16_f32 v119, v120, v121
	v_cvt_pk_f16_f32 v120, v102, v103
	v_cvt_pk_f16_f32 v121, v104, v105
	v_cvt_pk_f16_f32 v54, v54, v55
	v_cvt_pk_f16_f32 v55, v56, v57
	v_cvt_pk_f16_f32 v56, v38, v39
	v_cvt_pk_f16_f32 v57, v40, v41
	v_mov_b32_dpp v0, v118 row_ror:8 row_mask:0xf bank_mask:0xf
	v_mov_b32_dpp v1, v119 row_ror:8 row_mask:0xf bank_mask:0xf
	v_mov_b32_dpp v2, v120 row_ror:8 row_mask:0xf bank_mask:0xf
	v_mov_b32_dpp v3, v121 row_ror:8 row_mask:0xf bank_mask:0xf
	v_mov_b32_dpp v4, v54 row_ror:8 row_mask:0xf bank_mask:0xf
	v_mov_b32_dpp v5, v55 row_ror:8 row_mask:0xf bank_mask:0xf
	v_mov_b32_dpp v6, v56 row_ror:8 row_mask:0xf bank_mask:0xf
	v_mov_b32_dpp v7, v57 row_ror:8 row_mask:0xf bank_mask:0xf
	v_cndmask_b32_e32 v118, v118, v4, vcc
	v_cndmask_b32_e32 v119, v119, v5, vcc
	v_cndmask_b32_e32 v120, v120, v6, vcc
	v_cndmask_b32_e32 v121, v121, v7, vcc
	v_cndmask_b32_e32 v54, v0, v54, vcc
	v_cndmask_b32_e32 v55, v1, v55, vcc
	v_cndmask_b32_e32 v56, v2, v56, vcc
	v_cndmask_b32_e32 v57, v3, v57, vcc
	ds_bpermute_b32 v118, v13, v118
	ds_bpermute_b32 v119, v13, v119
	ds_bpermute_b32 v120, v13, v120
	ds_bpermute_b32 v121, v13, v121
	ds_bpermute_b32 v54, v13, v54
	ds_bpermute_b32 v55, v13, v55
	ds_bpermute_b32 v56, v13, v56
	ds_bpermute_b32 v57, v13, v57
	s_waitcnt lgkmcnt(8)
	v_add_u32_e32 v10, 0x18000, v20
	global_store_dwordx4 v20, v[126:129], s[70:71]
	global_store_dwordx4 v10, v[62:65], s[70:71]
	v_cvt_pk_f16_f32 v122, v122, v123
	v_cvt_pk_f16_f32 v123, v124, v125
	v_cvt_pk_f16_f32 v124, v106, v107
	v_cvt_pk_f16_f32 v125, v108, v109
	v_cvt_pk_f16_f32 v58, v58, v59
	v_cvt_pk_f16_f32 v59, v60, v61
	v_cvt_pk_f16_f32 v60, v42, v43
	v_cvt_pk_f16_f32 v61, v44, v45
	v_mov_b32_dpp v0, v122 row_ror:8 row_mask:0xf bank_mask:0xf
	v_mov_b32_dpp v1, v123 row_ror:8 row_mask:0xf bank_mask:0xf
	v_mov_b32_dpp v2, v124 row_ror:8 row_mask:0xf bank_mask:0xf
	v_mov_b32_dpp v3, v125 row_ror:8 row_mask:0xf bank_mask:0xf
	v_mov_b32_dpp v4, v58 row_ror:8 row_mask:0xf bank_mask:0xf
	v_mov_b32_dpp v5, v59 row_ror:8 row_mask:0xf bank_mask:0xf
	v_mov_b32_dpp v6, v60 row_ror:8 row_mask:0xf bank_mask:0xf
	v_mov_b32_dpp v7, v61 row_ror:8 row_mask:0xf bank_mask:0xf
	v_cndmask_b32_e32 v122, v122, v4, vcc
	v_cndmask_b32_e32 v123, v123, v5, vcc
	v_cndmask_b32_e32 v124, v124, v6, vcc
	v_cndmask_b32_e32 v125, v125, v7, vcc
	v_cndmask_b32_e32 v58, v0, v58, vcc
	v_cndmask_b32_e32 v59, v1, v59, vcc
	v_cndmask_b32_e32 v60, v2, v60, vcc
	v_cndmask_b32_e32 v61, v3, v61, vcc
	ds_bpermute_b32 v122, v13, v122
	ds_bpermute_b32 v123, v13, v123
	ds_bpermute_b32 v124, v13, v124
	ds_bpermute_b32 v125, v13, v125
	ds_bpermute_b32 v58, v13, v58
	ds_bpermute_b32 v59, v13, v59
	ds_bpermute_b32 v60, v13, v60
	ds_bpermute_b32 v61, v13, v61
	s_waitcnt lgkmcnt(8)
	v_add_u32_e32 v10, 0x18000, v21
	global_store_dwordx4 v21, v[118:121], s[70:71]
	global_store_dwordx4 v10, v[54:57], s[70:71]
	v_cvt_pk_f16_f32 v114, v114, v115
	v_cvt_pk_f16_f32 v115, v116, v117
	v_cvt_pk_f16_f32 v116, v98, v99
	v_cvt_pk_f16_f32 v117, v100, v101
	v_cvt_pk_f16_f32 v50, v50, v51
	v_cvt_pk_f16_f32 v51, v52, v53
	v_cvt_pk_f16_f32 v52, v34, v35
	v_cvt_pk_f16_f32 v53, v36, v37
	v_mov_b32_dpp v0, v114 row_ror:8 row_mask:0xf bank_mask:0xf
	v_mov_b32_dpp v1, v115 row_ror:8 row_mask:0xf bank_mask:0xf
	v_mov_b32_dpp v2, v116 row_ror:8 row_mask:0xf bank_mask:0xf
	v_mov_b32_dpp v3, v117 row_ror:8 row_mask:0xf bank_mask:0xf
	v_mov_b32_dpp v4, v50 row_ror:8 row_mask:0xf bank_mask:0xf
	v_mov_b32_dpp v5, v51 row_ror:8 row_mask:0xf bank_mask:0xf
	v_mov_b32_dpp v6, v52 row_ror:8 row_mask:0xf bank_mask:0xf
	v_mov_b32_dpp v7, v53 row_ror:8 row_mask:0xf bank_mask:0xf
	v_cndmask_b32_e32 v114, v114, v4, vcc
	v_cndmask_b32_e32 v115, v115, v5, vcc
	v_cndmask_b32_e32 v116, v116, v6, vcc
	v_cndmask_b32_e32 v117, v117, v7, vcc
	v_cndmask_b32_e32 v50, v0, v50, vcc
	v_cndmask_b32_e32 v51, v1, v51, vcc
	v_cndmask_b32_e32 v52, v2, v52, vcc
	v_cndmask_b32_e32 v53, v3, v53, vcc
	ds_bpermute_b32 v114, v13, v114
	ds_bpermute_b32 v115, v13, v115
	ds_bpermute_b32 v116, v13, v116
	ds_bpermute_b32 v117, v13, v117
	ds_bpermute_b32 v50, v13, v50
	ds_bpermute_b32 v51, v13, v51
	ds_bpermute_b32 v52, v13, v52
	ds_bpermute_b32 v53, v13, v53
	s_waitcnt lgkmcnt(8)
	v_add_u32_e32 v10, 0x18000, v22
	global_store_dwordx4 v22, v[122:125], s[70:71]
	global_store_dwordx4 v10, v[58:61], s[70:71]
	s_waitcnt lgkmcnt(0)
	v_add_u32_e32 v10, 0x18000, v23
	global_store_dwordx4 v23, v[114:117], s[70:71]
	global_store_dwordx4 v10, v[50:53], s[70:71]
	s_mov_b64 s[4:5], 0
